# opt24: NSA unit tile write: 8 LDS reads issued together with one wait instead of a read-wait-store ladder
# speedup vs baseline: 1.0043x; 1.0043x over previous
; #define LDS_WAIT() asm volatile("s_waitcnt lgkmcnt(0)" ::: "memory")
; __device__ __forceinline__ float shx(float v, int m) { return __shfl_xor(v, m); }
; __device__ __forceinline__ void a_unit(const ACtx& X, int b, int t0, float* ldsw, int lane) {
;     ...
;         for (int s_ = 0; s_ < 2; ++s_) {
;             const int h = 2 * s_ + (c >> 3);
;             float ls = l[s_]; ls += shx(ls, 16); ls += shx(ls, 32);
;             const float gwv = (float)P[(rowb + tq) * NPROJ + 38 * 64 + h * 3 + 2] / ls;
; #pragma unroll
;             for (int dt = 0; dt < 4; ++dt)
; #pragma unroll
;                 for (int r = 0; r < 4; ++r) outT[(q8 * 4 + h) * OTS + 16 * dt + 4 * g + r] += gwv * o[s_][dt][r];
;         }
;         LDS_WAIT(); __builtin_amdgcn_wave_barrier();
;     }
; #pragma unroll
;     for (int q = 0; q < 8; ++q) {
;         const f32x4 v = *(const f32x4*)(outT + (q * 4 + (lane >> 4)) * OTS + 4 * (lane & 15));
;         u32x2 pk; pk.x = pg8::pkh(v[0], v[1]); pk.y = pg8::pkh(v[2], v[3]);
;         *(u32x2*)(X.mix + (rowb + t0 + q) * D + 4 * lane) = pk;
;     }
.LBB0_687:
	ds_bpermute_b32 v34, v173, v151
	v_mov_b32_e32 v149, v1
	s_or_b32 s96, s96, s93
	v_readlane_b32 s10, v253, 34
	v_readlane_b32 s11, v253, 35
	s_waitcnt lgkmcnt(0)
	v_add_f32_e32 v34, v151, v34
	ds_bpermute_b32 v35, v222, v34
	v_mov_b32_e32 v151, v1
	s_waitcnt lgkmcnt(0)
	v_add_f32_e32 v36, v34, v35
	v_lshl_add_u64 v[34:35], v[152:153], 0, v[148:149]
	v_add_co_u32_e32 v38, vcc, 0x1000, v34
	s_nop 1
	v_addc_co_u32_e32 v39, vcc, 0, v35, vcc
	flat_load_ushort v34, v[38:39] offset:772
	s_waitcnt vmcnt(0) lgkmcnt(0)
	v_cvt_f32_f16_e32 v34, v34
	v_div_scale_f32 v35, s[2:3], v36, v36, v34
	v_rcp_f32_e32 v37, v35
	s_nop 0
	v_fma_f32 v40, -v35, v37, 1.0
	v_fmac_f32_e32 v37, v40, v37
	v_div_scale_f32 v40, vcc, v34, v36, v34
	v_mul_f32_e32 v41, v40, v37
	v_fma_f32 v42, -v35, v41, v40
	v_fmac_f32_e32 v41, v42, v37
	v_fma_f32 v35, -v35, v41, v40
	v_div_fmas_f32 v35, v35, v37, v41
	v_div_fixup_f32 v40, v35, v36, v34
	ds_read_b128 v[34:37], v217
	s_waitcnt lgkmcnt(0)
	v_pk_fma_f32 v[30:31], v[30:31], v[40:41], v[34:35] op_sel_hi:[1,0,1]
	v_pk_fma_f32 v[32:33], v[32:33], v[40:41], v[36:37] op_sel_hi:[1,0,1]
	ds_write_b128 v217, v[30:33]
	ds_read_b128 v[30:33], v217 offset:64
	s_waitcnt lgkmcnt(0)
	v_pk_fma_f32 v[26:27], v[26:27], v[40:41], v[30:31] op_sel_hi:[1,0,1]
	v_pk_fma_f32 v[28:29], v[28:29], v[40:41], v[32:33] op_sel_hi:[1,0,1]
	ds_write_b128 v217, v[26:29] offset:64
	ds_read_b128 v[26:29], v217 offset:128
	s_waitcnt lgkmcnt(0)
	v_pk_fma_f32 v[22:23], v[22:23], v[40:41], v[26:27] op_sel_hi:[1,0,1]
	v_pk_fma_f32 v[24:25], v[24:25], v[40:41], v[28:29] op_sel_hi:[1,0,1]
	ds_write_b128 v217, v[22:25] offset:128
	ds_read_b128 v[22:25], v217 offset:192
	s_waitcnt lgkmcnt(0)
	v_pk_fma_f32 v[18:19], v[18:19], v[40:41], v[22:23] op_sel_hi:[1,0,1]
	v_pk_fma_f32 v[20:21], v[20:21], v[40:41], v[24:25] op_sel_hi:[1,0,1]
	ds_write_b128 v217, v[18:21] offset:192
	ds_bpermute_b32 v18, v173, v147
	s_waitcnt lgkmcnt(0)
	v_add_f32_e32 v18, v147, v18
	ds_bpermute_b32 v19, v222, v18
	s_waitcnt lgkmcnt(0)
	v_add_f32_e32 v18, v18, v19
	flat_load_ushort v19, v[38:39] offset:784
	s_waitcnt vmcnt(0) lgkmcnt(0)
	v_cvt_f32_f16_e32 v19, v19
	v_div_scale_f32 v20, s[2:3], v18, v18, v19
	v_rcp_f32_e32 v21, v20
	s_lshl_b64 s[2:3], s[96:97], 11
	s_add_u32 s2, s10, s2
	s_addc_u32 s3, s11, s3
	v_fma_f32 v22, -v20, v21, 1.0
	v_fmac_f32_e32 v21, v22, v21
	v_div_scale_f32 v22, vcc, v19, v18, v19
	v_mul_f32_e32 v23, v22, v21
	v_fma_f32 v24, -v20, v23, v22
	v_fmac_f32_e32 v23, v24, v21
	v_fma_f32 v20, -v20, v23, v22
	v_div_fmas_f32 v20, v20, v21, v23
	v_div_fixup_f32 v22, v20, v18, v19
	ds_read_b128 v[18:21], v218
	s_waitcnt lgkmcnt(0)
	v_pk_fma_f32 v[14:15], v[14:15], v[22:23], v[18:19] op_sel_hi:[1,0,1]
	v_pk_fma_f32 v[16:17], v[16:17], v[22:23], v[20:21] op_sel_hi:[1,0,1]
	ds_write_b128 v218, v[14:17]
	ds_read_b128 v[14:17], v218 offset:64
	s_waitcnt lgkmcnt(0)
	v_pk_fma_f32 v[10:11], v[10:11], v[22:23], v[14:15] op_sel_hi:[1,0,1]
	v_pk_fma_f32 v[12:13], v[12:13], v[22:23], v[16:17] op_sel_hi:[1,0,1]
	ds_write_b128 v218, v[10:13] offset:64
	ds_read_b128 v[10:13], v218 offset:128
	s_waitcnt lgkmcnt(0)
	v_pk_fma_f32 v[6:7], v[6:7], v[22:23], v[10:11] op_sel_hi:[1,0,1]
	v_pk_fma_f32 v[8:9], v[8:9], v[22:23], v[12:13] op_sel_hi:[1,0,1]
	ds_write_b128 v218, v[6:9] offset:128
	ds_read_b128 v[6:9], v218 offset:192
	s_waitcnt lgkmcnt(0)
	v_pk_fma_f32 v[2:3], v[2:3], v[22:23], v[6:7] op_sel_hi:[1,0,1]
	v_pk_fma_f32 v[4:5], v[4:5], v[22:23], v[8:9] op_sel_hi:[1,0,1]
	ds_write_b128 v218, v[2:5] offset:192
	s_waitcnt lgkmcnt(0)
	v_lshl_add_u64 v[6:7], s[2:3], 0, v[150:151]
	ds_read_b128 v[10:13], v221
	ds_read_b128 v[14:17], v221 offset:1088
	ds_read_b128 v[18:21], v221 offset:2176
	ds_read_b128 v[22:25], v221 offset:3264
	ds_read_b128 v[26:29], v221 offset:4352
	ds_read_b128 v[30:33], v221 offset:5440
	ds_read_b128 v[34:37], v221 offset:6528
	ds_read_b128 v[38:41], v221 offset:7616
	s_movk_i32 s100, 0x1000
	s_mov_b32 s101, 0
	v_lshl_add_u64 v[8:9], v[6:7], 0, s[100:101]
	v_lshl_add_u64 v[2:3], v[8:9], 0, s[100:101]
	v_lshl_add_u64 v[4:5], v[2:3], 0, s[100:101]
	s_waitcnt lgkmcnt(0)
	v_cvt_pk_f16_f32 v10, v10, v11
	v_cvt_pk_f16_f32 v11, v12, v13
	v_cvt_pk_f16_f32 v14, v14, v15
	v_cvt_pk_f16_f32 v15, v16, v17
	v_cvt_pk_f16_f32 v18, v18, v19
	v_cvt_pk_f16_f32 v19, v20, v21
	v_cvt_pk_f16_f32 v22, v22, v23
	v_cvt_pk_f16_f32 v23, v24, v25
	v_cvt_pk_f16_f32 v26, v26, v27
	v_cvt_pk_f16_f32 v27, v28, v29
	v_cvt_pk_f16_f32 v30, v30, v31
	v_cvt_pk_f16_f32 v31, v32, v33
	v_cvt_pk_f16_f32 v34, v34, v35
	v_cvt_pk_f16_f32 v35, v36, v37
	v_cvt_pk_f16_f32 v38, v38, v39
	v_cvt_pk_f16_f32 v39, v40, v41
	flat_store_dwordx2 v[6:7], v[10:11]
	flat_store_dwordx2 v[6:7], v[14:15] offset:2048
	flat_store_dwordx2 v[8:9], v[18:19]
	flat_store_dwordx2 v[8:9], v[22:23] offset:2048
	flat_store_dwordx2 v[2:3], v[26:27]
	flat_store_dwordx2 v[2:3], v[30:31] offset:2048
	flat_store_dwordx2 v[4:5], v[34:35]
	flat_store_dwordx2 v[4:5], v[38:39] offset:2048
	s_waitcnt lgkmcnt(0)
